# E3 out-projection: residual hi/lo tile loaded inside the k-loop (one 16x16 group per k-step) and added into the f32 accumulators there, epilogue only splits and stores; attention epilogue: gate loads
# baseline (speedup 1.0000x reference)
;     ...
;   if (bid < ntiles) {
;     const int my_tiles = (ntiles - 1 - bid) / G + 1;
;     const int last_id = bid + (my_tiles - 1) * G;
;     const int S = my_tiles * nk;
;     f32x4 acc[4][TI];
; #pragma unroll
;     for (int a = 0; a < 4; ++a)
; #pragma unroll
;       for (int b = 0; b < TI; ++b) acc[a][b] = (f32x4){0.f, 0.f, 0.f, 0.f};
;     u32x4 ra0[4], rb0[2], ra1[4], rb1[2];
;     u32x4 rx0 = (u32x4){0u, 0u, 0u, 0u}, rx1 = (u32x4){0u, 0u, 0u, 0u};
;     float ss[5] = {0.f, 0.f, 0.f, 0.f, 0.f};
;     int l_id = bid, l_kt = 0, c_id = bid, c_kt = 0, st_kt = 0;
;     const int srow = tid >> 3;
;     const int soff = srow * 128 + (((tid & 7) ^ (srow & 7)) << 4);
;     const int wrow = tid5 >> 3;
;     const int woff = wrow * 128 + (((tid5 & 7) ^ (wrow & 7)) << 4);
;     ...
; #pragma unroll 1
;     for (int s = 0; s < S; s += 2) {
;       issue(ra0, rb0, rx0);
;       compute(0);
;       store(ra1, rb1, rx1, 1);
;       __syncthreads();
;       issue(ra1, rb1, rx1);
;       compute(1);
;       c_kt += 2;
;       if (c_kt == nk) { c_kt = 0; tile_end(); }
;       store(ra0, rb0, rx0, 0);
;       __syncthreads();
;     }
.LBB0_1777:
	s_or_b64 exec, exec, s[6:7]
	s_lshl_b32 s31, s8, 5
	s_add_i32 s31, s31, 32
	s_cmp_lt_i32 s31, 1
	s_waitcnt lgkmcnt(0)
	s_barrier
	s_cbranch_scc1 .LBB0_1824
	v_and_b32_e32 v11, 15, v10
	v_ashrrev_i32_e32 v8, 7, v10
	v_bfe_u32 v9, v10, 6, 1
	v_lshlrev_b32_e32 v15, 7, v11
	v_lshrrev_b32_e32 v13, 4, v10
	v_lshl_or_b32 v37, v9, 13, v15
	v_lshl_or_b32 v180, v8, 13, v15
	v_and_b32_e32 v15, 7, v10
	v_bitop3_b32 v13, v13, v15, 3 bitop3:0x6c
	v_bfe_u32 v14, v10, 4, 2
	v_lshlrev_b32_e32 v181, 4, v13
	v_and_b32_e32 v13, 64, v10
	s_add_u32 s50, s44, 0x2040000
	v_cmp_ne_u32_e64 s[40:41], 0, v13
	v_or_b32_e32 v13, 4, v14
	v_bitop3_b32 v15, v14, v15, 4 bitop3:0x36
	v_lshlrev_b32_e32 v10, 4, v10
	s_addc_u32 s51, s45, 0
	v_add_u32_e32 v179, s9, v37
	v_lshlrev_b32_e32 v37, 4, v14
	v_lshlrev_b32_e32 v182, 4, v15
	v_lshlrev_b32_e32 v38, 4, v13
	v_and_b32_e32 v10, 0x70, v10
	v_lshlrev_b32_e32 v183, 6, v8
	v_lshlrev_b32_e32 v172, 2, v14
	v_or_b32_e32 v8, v9, v11
	v_mov_b32_e32 v13, v12
	v_mov_b32_e32 v14, v12
	v_mov_b32_e32 v15, v12
	s_add_u32 s54, s44, 0xa344000
	v_lshl_or_b32 v184, v9, 6, v11
	v_cmp_eq_u32_e32 vcc, 0, v11
	v_cmp_eq_u32_e64 s[42:43], 0, v8
	v_mov_b32_e32 v68, 0
	v_add_u32_e32 v185, v36, v37
	v_add_u32_e32 v201, v36, v38
	v_add_u32_e32 v202, v36, v10
	v_mov_b64_e32 v[8:9], v[12:13]
	v_mov_b64_e32 v[38:39], v[14:15]
	v_mov_b64_e32 v[90:91], v[14:15]
	v_mov_b64_e32 v[110:111], v[14:15]
	s_addc_u32 s55, s45, 0
	s_mov_b32 s56, 0
	s_mov_b32 s6, 2
	s_and_b64 s[52:53], vcc, s[40:41]
	v_mov_b64_e32 v[10:11], v[14:15]
	v_mov_b64_e32 v[36:37], v[12:13]
	v_mov_b64_e32 v[88:89], v[12:13]
	v_mov_b64_e32 v[108:109], v[12:13]
	s_mov_b32 s8, 0
	s_mov_b32 s7, s12
	v_mov_b32_e32 v69, v68
	v_mov_b32_e32 v70, v68
	v_mov_b32_e32 v71, v68
	v_mov_b32_e32 v72, v68
	v_mov_b32_e32 v73, v68
	v_mov_b32_e32 v74, v68
	v_mov_b32_e32 v75, v68
	v_mov_b32_e32 v76, v68
	v_mov_b32_e32 v77, v68
	v_mov_b32_e32 v78, v68
	v_mov_b32_e32 v79, v68
	v_mov_b32_e32 v80, v68
	v_mov_b32_e32 v81, v68
	v_mov_b32_e32 v82, v68
	v_mov_b32_e32 v83, v68
	v_mov_b32_e32 v84, v68
	v_mov_b32_e32 v85, v68
	v_mov_b32_e32 v86, v68
	v_mov_b32_e32 v87, v68
	v_mov_b32_e32 v92, v68
	v_mov_b32_e32 v93, v68
	v_mov_b32_e32 v94, v68
	v_mov_b32_e32 v95, v68
	v_mov_b32_e32 v96, v68
	v_mov_b32_e32 v97, v68
	v_mov_b32_e32 v98, v68
	v_mov_b32_e32 v99, v68
	v_mov_b32_e32 v100, v68
	v_mov_b32_e32 v101, v68
	v_mov_b32_e32 v102, v68
	v_mov_b32_e32 v103, v68
	v_mov_b32_e32 v104, v68
	v_mov_b32_e32 v105, v68
	v_mov_b32_e32 v106, v68
	v_mov_b32_e32 v107, v68
	v_mov_b32_e32 v112, v68
	v_mov_b32_e32 v113, v68
	v_mov_b32_e32 v114, v68
	v_mov_b32_e32 v115, v68
	v_mov_b32_e32 v116, v68
	v_mov_b32_e32 v117, v68
	v_mov_b32_e32 v118, v68
	v_mov_b32_e32 v119, v68
	v_mov_b32_e32 v120, v68
	v_mov_b32_e32 v121, v68
	v_mov_b32_e32 v122, v68
	v_mov_b32_e32 v123, v68
	v_mov_b32_e32 v124, v68
	v_mov_b32_e32 v125, v68
	v_mov_b32_e32 v126, v68
	v_mov_b32_e32 v127, v68
	v_mov_b32_e32 v128, v68
	v_mov_b32_e32 v129, v68
	v_mov_b32_e32 v130, v68
	v_mov_b32_e32 v131, v68
	v_mov_b32_e32 v132, v68
	v_mov_b32_e32 v133, v68
	v_mov_b32_e32 v134, v68
	v_mov_b32_e32 v135, v68
	v_mov_b32_e32 v136, v68
	v_mov_b32_e32 v137, v68
	v_mov_b32_e32 v138, v68
	v_mov_b32_e32 v139, v68
	s_lshr_b32 s100, s12, 6
	s_lshl_b32 s100, s100, 3
	s_and_b32 s101, s12, 7
	s_or_b32 s100, s100, s101
	s_mulk_i32 s100, 0x102
	s_add_i32 s100, s100, s30
	s_lshl_b32 s100, s100, 11
	s_bfe_u32 s101, s12, 0x30003
	s_lshl_b32 s101, s101, 8
	s_add_i32 s100, s100, s101
	v_or_b32_e32 v251, v183, v172
	v_lshlrev_b32_e32 v251, 1, v251
	v_lshl_add_u32 v251, v184, 11, v251
	global_load_dwordx2 v[246:247], v12, s[44:45]
	global_load_dwordx2 v[248:249], v12, s[50:51]
	s_branch .LBB0_1780
.LBB0_1779:
	s_or_b64 exec, exec, s[4:5]
	s_cmp_gt_u32 s8, 16
	s_cbranch_scc1 .Lres_e3b_done
	s_cmp_lt_u32 s8, 2
	s_cbranch_scc1 .Lres_e3b_done
	s_waitcnt vmcnt(9)
	s_cmp_eq_u32 s8, 2
	s_cbranch_scc1 .Lres_e3b_g0
	s_cmp_eq_u32 s8, 4
	s_cbranch_scc1 .Lres_e3b_g2
	s_cmp_eq_u32 s8, 6
	s_cbranch_scc1 .Lres_e3b_g4
	s_cmp_eq_u32 s8, 8
	s_cbranch_scc1 .Lres_e3b_g6
	s_cmp_eq_u32 s8, 10
	s_cbranch_scc1 .Lres_e3b_g8
	s_cmp_eq_u32 s8, 12
	s_cbranch_scc1 .Lres_e3b_g10
	s_cmp_eq_u32 s8, 14
	s_cbranch_scc1 .Lres_e3b_g12
	s_branch .Lres_e3b_g14
; __device__ __forceinline__ float bflo(unsigned v) { return __uint_as_float(v << 16); }
; __device__ __forceinline__ float bfhi(unsigned v) { return __uint_as_float(v & 0xffff0000u); }
; template <int EPI, int TI>
; __device__ __forceinline__ void gemm_epilogue(const WS& ws, const f32x4 (&acc)[4][TI], const float (&rs)[TI], int tok0, int n0,
;                                               int wm, int wn, int lr, int lq, bool dry) {
;     ...
;         if (!(ti < 4 || (lr == 0 && (ni >> 1) == wn))) continue;
;         const size_t off = (size_t)(ti < 4 ? tokr(ti) : tok0 + 128) * 1024 + nw + ni * 16 + 4 * lq;
;         const u32x2 hi = *(const u32x2*)(ws.HHI + off), lo = *(const u32x2*)(ws.HLO + off);
;         const float h0 = bflo(hi.x) + bflo(lo.x) + acc[ni][ti][0], h1 = bfhi(hi.x) + bfhi(lo.x) + acc[ni][ti][1];
;         const float h2 = bflo(hi.y) + bflo(lo.y) + acc[ni][ti][2], h3 = bfhi(hi.y) + bfhi(lo.y) + acc[ni][ti][3];
.Lres_e3b_g0:
	s_nop 7
	v_lshlrev_b32_e32 v252, 16, v242
	v_and_b32_e32 v253, 0xffff0000, v242
	v_lshlrev_b32_e32 v254, 16, v243
	v_and_b32_e32 v255, 0xffff0000, v243
	v_lshlrev_b32_e32 v242, 16, v244
	v_and_b32_e32 v243, 0xffff0000, v244
	v_lshlrev_b32_e32 v244, 16, v245
	v_and_b32_e32 v245, 0xffff0000, v245
	v_pk_add_f32 v[252:253], v[252:253], v[242:243]
	v_pk_add_f32 v[254:255], v[254:255], v[244:245]
	v_pk_add_f32 v[136:137], v[136:137], v[252:253]
	v_pk_add_f32 v[138:139], v[138:139], v[254:255]
	s_branch .Lres_e3b_done
.Lres_e3b_g2:
	s_nop 7
	v_lshlrev_b32_e32 v252, 16, v242
	v_and_b32_e32 v253, 0xffff0000, v242
	v_lshlrev_b32_e32 v254, 16, v243
	v_and_b32_e32 v255, 0xffff0000, v243
	v_lshlrev_b32_e32 v242, 16, v244
	v_and_b32_e32 v243, 0xffff0000, v244
	v_lshlrev_b32_e32 v244, 16, v245
	v_and_b32_e32 v245, 0xffff0000, v245
	v_pk_add_f32 v[252:253], v[252:253], v[242:243]
	v_pk_add_f32 v[254:255], v[254:255], v[244:245]
	v_pk_add_f32 v[100:101], v[100:101], v[252:253]
	v_pk_add_f32 v[102:103], v[102:103], v[254:255]
	s_branch .Lres_e3b_done
.Lres_e3b_g4:
	s_nop 7
	v_lshlrev_b32_e32 v252, 16, v242
	v_and_b32_e32 v253, 0xffff0000, v242
	v_lshlrev_b32_e32 v254, 16, v243
	v_and_b32_e32 v255, 0xffff0000, v243
	v_lshlrev_b32_e32 v242, 16, v244
	v_and_b32_e32 v243, 0xffff0000, v244
	v_lshlrev_b32_e32 v244, 16, v245
	v_and_b32_e32 v245, 0xffff0000, v245
	v_pk_add_f32 v[252:253], v[252:253], v[242:243]
	v_pk_add_f32 v[254:255], v[254:255], v[244:245]
	v_pk_add_f32 v[132:133], v[132:133], v[252:253]
	v_pk_add_f32 v[134:135], v[134:135], v[254:255]
	s_branch .Lres_e3b_done
.Lres_e3b_g6:
	s_nop 7
	v_lshlrev_b32_e32 v252, 16, v242
	v_and_b32_e32 v253, 0xffff0000, v242
	v_lshlrev_b32_e32 v254, 16, v243
	v_and_b32_e32 v255, 0xffff0000, v243
	v_lshlrev_b32_e32 v242, 16, v244
	v_and_b32_e32 v243, 0xffff0000, v244
	v_lshlrev_b32_e32 v244, 16, v245
	v_and_b32_e32 v245, 0xffff0000, v245
	v_pk_add_f32 v[252:253], v[252:253], v[242:243]
	v_pk_add_f32 v[254:255], v[254:255], v[244:245]
	v_pk_add_f32 v[96:97], v[96:97], v[252:253]
	v_pk_add_f32 v[98:99], v[98:99], v[254:255]
	s_branch .Lres_e3b_done
.Lres_e3b_g8:
	s_nop 7
	v_lshlrev_b32_e32 v252, 16, v242
	v_and_b32_e32 v253, 0xffff0000, v242
	v_lshlrev_b32_e32 v254, 16, v243
	v_and_b32_e32 v255, 0xffff0000, v243
	v_lshlrev_b32_e32 v242, 16, v244
	v_and_b32_e32 v243, 0xffff0000, v244
	v_lshlrev_b32_e32 v244, 16, v245
	v_and_b32_e32 v245, 0xffff0000, v245
	v_pk_add_f32 v[252:253], v[252:253], v[242:243]
	v_pk_add_f32 v[254:255], v[254:255], v[244:245]
	v_pk_add_f32 v[128:129], v[128:129], v[252:253]
	v_pk_add_f32 v[130:131], v[130:131], v[254:255]
	s_branch .Lres_e3b_done
.Lres_e3b_g10:
	s_nop 7
	v_lshlrev_b32_e32 v252, 16, v242
	v_and_b32_e32 v253, 0xffff0000, v242
	v_lshlrev_b32_e32 v254, 16, v243
	v_and_b32_e32 v255, 0xffff0000, v243
	v_lshlrev_b32_e32 v242, 16, v244
	v_and_b32_e32 v243, 0xffff0000, v244
	v_lshlrev_b32_e32 v244, 16, v245
	v_and_b32_e32 v245, 0xffff0000, v245
	v_pk_add_f32 v[252:253], v[252:253], v[242:243]
	v_pk_add_f32 v[254:255], v[254:255], v[244:245]
	v_pk_add_f32 v[92:93], v[92:93], v[252:253]
	v_pk_add_f32 v[94:95], v[94:95], v[254:255]
	s_branch .Lres_e3b_done
.Lres_e3b_g12:
	s_nop 7
	v_lshlrev_b32_e32 v252, 16, v242
	v_and_b32_e32 v253, 0xffff0000, v242
	v_lshlrev_b32_e32 v254, 16, v243
	v_and_b32_e32 v255, 0xffff0000, v243
	v_lshlrev_b32_e32 v242, 16, v244
	v_and_b32_e32 v243, 0xffff0000, v244
	v_lshlrev_b32_e32 v244, 16, v245
	v_and_b32_e32 v245, 0xffff0000, v245
	v_pk_add_f32 v[252:253], v[252:253], v[242:243]
	v_pk_add_f32 v[254:255], v[254:255], v[244:245]
	v_pk_add_f32 v[124:125], v[124:125], v[252:253]
	v_pk_add_f32 v[126:127], v[126:127], v[254:255]
	s_branch .Lres_e3b_done
.Lres_e3b_g14:
	s_nop 7
	v_lshlrev_b32_e32 v252, 16, v242
	v_and_b32_e32 v253, 0xffff0000, v242
	v_lshlrev_b32_e32 v254, 16, v243
	v_and_b32_e32 v255, 0xffff0000, v243
	v_lshlrev_b32_e32 v242, 16, v244
	v_and_b32_e32 v243, 0xffff0000, v244
	v_lshlrev_b32_e32 v244, 16, v245
	v_and_b32_e32 v245, 0xffff0000, v245
	v_pk_add_f32 v[252:253], v[252:253], v[242:243]
	v_pk_add_f32 v[254:255], v[254:255], v[244:245]
	v_pk_add_f32 v[84:85], v[84:85], v[252:253]
	v_pk_add_f32 v[86:87], v[86:87], v[254:255]
	s_branch .Lres_e3b_done
.Lres_e3b_done:
	s_load_dwordx2 s[4:5], s[0:1], 0x110
	s_add_i32 s58, s58, 1
	s_cmp_eq_u32 s58, 32
	s_cselect_b32 s6, 0, s58
	s_waitcnt lgkmcnt(0)
	s_cselect_b32 s4, s4, 0
	s_add_i32 s7, s4, s57
	s_add_i32 s56, s56, 2
	s_cmp_lt_i32 s56, s31
	s_barrier
	s_cbranch_scc0 .LBB0_1824

; #define MFMA16(a, b, c) __builtin_amdgcn_mfma_f32_16x16x32_bf16((a), (b), (c), 0, 0, 0)
;     ...
;     auto issue = [&](u32x4 (&ra)[4], u32x4 (&rb)[2], u32x4& rx) {
;       const int idc = l_id < last_id ? l_id : last_id;
;       int mt, nt; if (TMAP == 1) rem_tile(idc, mt, nt); else tile_of(idc, ntn, mt, nt);
;       const bf16_t* A = (l_kt < ktsplit) ? A0 : A1;
;       const int kk = (l_kt < ktsplit) ? l_kt : l_kt - ktsplit;
;       const int arow = mt * 2 * BMH + hh * BMH + srow;
;       const bf16_t* akb = A + kk * kstride + (tid & 7) * 8;
;       const bf16_t* wp = W + (size_t)(nt * 128 + wrow) * K + l_kt * 64 + (tid5 & 7) * 8;
; #pragma unroll
;       for (int i = 0; i < 4; ++i) {
;         int r = arow + 32 * i; r = r < M_ ? r : M_ - 1;
;         ra[i] = *(const u32x4*)(akb + (size_t)r * lda);
;       }
; #pragma unroll
;       for (int i = 0; i < 2; ++i) rb[i] = *(const u32x4*)(wp + (size_t)i * 64 * K);
;       if (TI == 5) rx = *(const u32x4*)(akb + (size_t)(arow - srow + 128) * lda);
;       if (++l_kt == nk) { l_kt = 0; l_id += G; }
;     };
;     ...
;     auto compute = [&](int buf) {
;       const unsigned char* Ab = As + buf * ASTG + (wn * 64 + lr) * 128;
;       const unsigned char* Ax = Ax0 + buf * 128;
;       const unsigned char* Bb = Bs + buf * 16384 + (wm * 64 + lr) * 128;
; #pragma unroll
;       for (int ks = 0; ks < 2; ++ks) {
;         if (TI == 5 && ks == 1) __builtin_amdgcn_sched_barrier(0);
;         const int sw = ((ks * 4 + lq) ^ (lr & 7)) << 4;
;         bf16x8 wf[4], xf[TI];
; #pragma unroll
;         for (int i = 0; i < 4; ++i) {
;           wf[i] = *(const bf16x8*)(Bb + i * 2048 + sw);
;           xf[i] = *(const bf16x8*)(Ab + i * 2048 + sw);
;         }
;         if (TI == 5) xf[TI - 1] = *(const bf16x8*)(Ax + ((ks * 4 + lq) << 4));
; #pragma unroll
;         for (int ni = 0; ni < 4; ++ni)
; #pragma unroll
;           for (int ti = 0; ti < 4; ++ti) acc[ni][ti] = MFMA16(wf[ni], xf[ti], acc[ni][ti]);
;         if (TI == 5) {
;           if (wn == 0) { acc[0][TI - 1] = MFMA16(wf[0], xf[TI - 1], acc[0][TI - 1]); acc[1][TI - 1] = MFMA16(wf[1], xf[TI - 1], acc[1][TI - 1]); }
;           else { acc[2][TI - 1] = MFMA16(wf[2], xf[TI - 1], acc[2][TI - 1]); acc[3][TI - 1] = MFMA16(wf[3], xf[TI - 1], acc[3][TI - 1]); }
;         }
;       }
.LBB0_1784:
	s_cmp_lt_i32 s6, 16
	s_cselect_b32 s5, 0, -16
	s_cselect_b32 s10, s47, s55
	s_cselect_b32 s11, s46, s54
	s_add_i32 s5, s5, s6
	v_add_u32_e32 v13, v180, v181
	v_add_u32_e32 v14, s4, v176
	s_lshl_b32 s4, s5, 6
	ds_read_b128 v[148:151], v13 offset:32768
	s_ashr_i32 s5, s4, 31
	s_lshl_b64 s[4:5], s[4:5], 1
	s_add_u32 s4, s11, s4
	v_add_u32_e32 v15, v179, v181
	v_min_i32_e32 v42, 0x405f, v14
	s_addc_u32 s5, s10, s5
	v_mov_b32_e32 v169, v12
	ds_read_b128 v[56:59], v15
	ds_read_b128 v[152:155], v13 offset:34816
	s_waitcnt vmcnt(9)
	ds_read_b128 v[64:67], v15 offset:2048
	ds_read_b128 v[160:163], v15 offset:4096
	ds_read_b128 v[204:207], v15 offset:6144
	v_ashrrev_i32_e32 v43, 31, v42
	v_lshl_add_u64 v[208:209], s[4:5], 0, v[168:169]
	v_min_i32_e32 v40, 0x407f, v14
	v_lshlrev_b64 v[42:43], 11, v[42:43]
	v_ashrrev_i32_e32 v41, 31, v40
	v_lshl_add_u64 v[42:43], v[208:209], 0, v[42:43]
	v_lshlrev_b64 v[40:41], 11, v[40:41]
	v_add_co_u32_e32 v44, vcc, s82, v42
	v_lshl_add_u64 v[40:41], v[208:209], 0, v[40:41]
	s_nop 0
	v_addc_co_u32_e32 v45, vcc, 0, v43, vcc
	s_waitcnt lgkmcnt(1)
	v_mfma_f32_16x16x32_bf16 v[140:143], v[148:151], v[160:163], v[128:131]
	global_load_dwordx4 v[40:43], v[40:41], off
	s_nop 0
	global_load_dwordx4 v[44:47], v[44:45], off
	ds_read_b128 v[128:131], v13 offset:36864
	ds_read_b128 v[156:159], v13 offset:38912
	v_min_i32_e32 v48, 0x403f, v14
	v_ashrrev_i32_e32 v49, 31, v48
	v_lshl_add_u32 v60, s9, 7, v174
	v_lshlrev_b64 v[48:49], 11, v[48:49]
	v_min_i32_e32 v50, 0x401f, v14
	v_ashrrev_i32_e32 v61, 31, v60
	v_lshl_add_u64 v[48:49], v[208:209], 0, v[48:49]
	v_ashrrev_i32_e32 v51, 31, v50
	s_lshl_b32 s4, s6, 6
	v_add_co_u32_e32 v48, vcc, s2, v48
	v_lshlrev_b64 v[50:51], 11, v[50:51]
	v_lshlrev_b64 v[60:61], 12, v[60:61]
	s_ashr_i32 s5, s4, 31
	v_addc_co_u32_e32 v49, vcc, 0, v49, vcc
	v_lshl_add_u64 v[50:51], v[208:209], 0, v[50:51]
	s_mov_b32 s3, 0x30000
	v_lshl_add_u64 v[60:61], s[48:49], 0, v[60:61]
	v_sub_u32_e32 v14, v14, v173
	s_waitcnt lgkmcnt(1)
	v_mfma_f32_16x16x32_bf16 v[144:147], v[128:131], v[56:59], v[100:103]
	v_add_co_u32_e32 v52, vcc, s3, v50
	v_lshl_add_u64 v[60:61], s[4:5], 1, v[60:61]
	v_mov_b32_e32 v171, v12
	v_add_u32_e32 v100, 0x80, v14
	v_addc_co_u32_e32 v53, vcc, 0, v51, vcc
	v_lshl_add_u64 v[60:61], v[60:61], 0, v[170:171]
	s_mov_b32 s3, 0x40000
	v_ashrrev_i32_e32 v101, 31, v100
	v_mfma_f32_16x16x32_bf16 v[132:135], v[148:151], v[64:67], v[132:135]
	v_add_co_u32_e32 v62, vcc, s3, v60
	global_load_dwordx4 v[48:51], v[48:49], off
	s_nop 0
	global_load_dwordx4 v[52:55], v[52:53], off
	v_mfma_f32_16x16x32_bf16 v[116:119], v[152:155], v[64:67], v[116:119]
	v_addc_co_u32_e32 v63, vcc, 0, v61, vcc
	v_mfma_f32_16x16x32_bf16 v[96:99], v[128:131], v[64:67], v[96:99]
	s_waitcnt lgkmcnt(0)
	v_mfma_f32_16x16x32_bf16 v[76:79], v[156:159], v[64:67], v[76:79]
	v_lshlrev_b64 v[64:65], 11, v[100:101]
	v_lshl_add_u64 v[64:65], v[208:209], 0, v[64:65]
	v_mfma_f32_16x16x32_bf16 v[136:139], v[148:151], v[56:59], v[136:139]
	v_mfma_f32_16x16x32_bf16 v[120:123], v[152:155], v[56:59], v[120:123]
	v_mfma_f32_16x16x32_bf16 v[80:83], v[156:159], v[56:59], v[80:83]
	global_load_dwordx4 v[56:59], v[60:61], off
	s_nop 0
	global_load_dwordx4 v[60:63], v[62:63], off
	ds_read_b128 v[100:103], v185
	global_load_dwordx4 v[64:67], v[64:65], off
	s_lshr_b32 s101, s8, 2
	s_mulk_i32 s101, 0x7f80
	v_add_u32_e32 v250, s100, v251
	v_add_u32_e32 v250, s101, v250
	s_lshl_b32 s101, s8, 5
	v_add_u32_e32 v250, s101, v250
	s_cmp_lt_u32 s8, 16
	s_cselect_b32 s101, -1, 0
	v_and_b32_e32 v250, s101, v250
	global_load_dwordx2 v[242:243], v250, s[44:45]
	global_load_dwordx2 v[244:245], v250, s[50:51]
	v_mfma_f32_16x16x32_bf16 v[124:127], v[148:151], v[204:207], v[124:127]
	v_mfma_f32_16x16x32_bf16 v[112:115], v[152:155], v[160:163], v[112:115]
	v_mfma_f32_16x16x32_bf16 v[104:107], v[152:155], v[204:207], v[104:107]
	v_mfma_f32_16x16x32_bf16 v[92:95], v[128:131], v[160:163], v[92:95]
	v_mfma_f32_16x16x32_bf16 v[84:87], v[128:131], v[204:207], v[84:87]
	v_mfma_f32_16x16x32_bf16 v[72:75], v[156:159], v[160:163], v[72:75]
	v_mfma_f32_16x16x32_bf16 v[68:71], v[156:159], v[204:207], v[68:71]
	s_and_saveexec_b64 s[4:5], s[40:41]
	s_xor_b64 s[4:5], exec, s[4:5]
	s_cbranch_execz .LBB0_1786
	s_waitcnt lgkmcnt(0)
	v_mfma_f32_16x16x32_bf16 v[36:39], v[128:131], v[100:103], v[36:39]
	v_mfma_f32_16x16x32_bf16 v[8:11], v[156:159], v[100:103], v[8:11]

;     ...
;     auto store = [&](const u32x4 (&ra)[4], const u32x4 (&rb)[2], const u32x4& rx, int buf) {
; #pragma unroll
;       for (int i = 0; i < 4; ++i) {
;         if (RS) ss[i] += sumsq8(__builtin_bit_cast(bf16x8, ra[i]));
;         *(u32x4*)(As + buf * ASTG + i * 4096 + soff) = ra[i];
;       }
; #pragma unroll
;       for (int i = 0; i < 2; ++i) *(u32x4*)(Bs + buf * 16384 + i * 8192 + woff) = rb[i];
;       if (TI == 5) {
;         if (RS) ss[4] += sumsq8(__builtin_bit_cast(bf16x8, rx));
;         if (srow == 0) *(u32x4*)(Ax0 + buf * 128 + ((tid & 7) << 4)) = rx;
;       }
.LBB0_1792:
	s_or_b64 exec, exec, s[4:5]
	s_waitcnt vmcnt(17)
	ds_write_b128 v178, v[0:3] offset:16384
	s_waitcnt vmcnt(16)
	ds_write_b128 v178, v[4:7] offset:20480
	s_waitcnt vmcnt(15)
	ds_write_b128 v178, v[16:19] offset:24576
	s_waitcnt vmcnt(14)
	ds_write_b128 v178, v[20:23] offset:28672
	s_waitcnt vmcnt(13)
	ds_write_b128 v177, v[24:27] offset:49152
	s_waitcnt vmcnt(12)
	ds_write_b128 v177, v[28:31] offset:57344
	s_and_saveexec_b64 s[4:5], s[38:39]
	s_cbranch_execz .LBB0_1794
	s_waitcnt vmcnt(11)
	ds_write_b128 v202, v[32:35] offset:128

; __device__ __forceinline__ float bflo(unsigned v) { return __uint_as_float(v << 16); }
; __device__ __forceinline__ float bfhi(unsigned v) { return __uint_as_float(v & 0xffff0000u); }
; template <int EPI, int TI>
; __device__ __forceinline__ void gemm_epilogue(const WS& ws, const f32x4 (&acc)[4][TI], const float (&rs)[TI], int tok0, int n0,
;                                               int wm, int wn, int lr, int lq, bool dry) {
;     ...
;         if (!(ti < 4 || (lr == 0 && (ni >> 1) == wn))) continue;
;         const size_t off = (size_t)(ti < 4 ? tokr(ti) : tok0 + 128) * 1024 + nw + ni * 16 + 4 * lq;
;         const u32x2 hi = *(const u32x2*)(ws.HHI + off), lo = *(const u32x2*)(ws.HLO + off);
;         const float h0 = bflo(hi.x) + bflo(lo.x) + acc[ni][ti][0], h1 = bfhi(hi.x) + bfhi(lo.x) + acc[ni][ti][1];
;         const float h2 = bflo(hi.y) + bflo(lo.y) + acc[ni][ti][2], h3 = bfhi(hi.y) + bfhi(lo.y) + acc[ni][ti][3];
;     ...
;       issue(ra1, rb1, rx1);
;       compute(1);
;       c_kt += 2;
;       if (c_kt == nk) { c_kt = 0; tile_end(); }
;       store(ra0, rb0, rx0, 0);
.Lres_e3a_g1:
	s_nop 7
	v_lshlrev_b32_e32 v252, 16, v246
	v_and_b32_e32 v253, 0xffff0000, v246
	v_lshlrev_b32_e32 v254, 16, v247
	v_and_b32_e32 v255, 0xffff0000, v247
	v_lshlrev_b32_e32 v246, 16, v248
	v_and_b32_e32 v247, 0xffff0000, v248
	v_lshlrev_b32_e32 v248, 16, v249
	v_and_b32_e32 v249, 0xffff0000, v249
	v_pk_add_f32 v[252:253], v[252:253], v[246:247]
	v_pk_add_f32 v[254:255], v[254:255], v[248:249]
	v_pk_add_f32 v[120:121], v[120:121], v[252:253]
	v_pk_add_f32 v[122:123], v[122:123], v[254:255]
	s_branch .Lres_e3a_done
.Lres_e3a_g3:
	s_nop 7
	v_lshlrev_b32_e32 v252, 16, v246
	v_and_b32_e32 v253, 0xffff0000, v246
	v_lshlrev_b32_e32 v254, 16, v247
	v_and_b32_e32 v255, 0xffff0000, v247
	v_lshlrev_b32_e32 v246, 16, v248
	v_and_b32_e32 v247, 0xffff0000, v248
	v_lshlrev_b32_e32 v248, 16, v249
	v_and_b32_e32 v249, 0xffff0000, v249
	v_pk_add_f32 v[252:253], v[252:253], v[246:247]
	v_pk_add_f32 v[254:255], v[254:255], v[248:249]
	v_pk_add_f32 v[80:81], v[80:81], v[252:253]
	v_pk_add_f32 v[82:83], v[82:83], v[254:255]
	s_branch .Lres_e3a_done
.Lres_e3a_g5:
	s_nop 7
	v_lshlrev_b32_e32 v252, 16, v246
	v_and_b32_e32 v253, 0xffff0000, v246
	v_lshlrev_b32_e32 v254, 16, v247
	v_and_b32_e32 v255, 0xffff0000, v247
	v_lshlrev_b32_e32 v246, 16, v248
	v_and_b32_e32 v247, 0xffff0000, v248
	v_lshlrev_b32_e32 v248, 16, v249
	v_and_b32_e32 v249, 0xffff0000, v249
	v_pk_add_f32 v[252:253], v[252:253], v[246:247]
	v_pk_add_f32 v[254:255], v[254:255], v[248:249]
	v_pk_add_f32 v[116:117], v[116:117], v[252:253]
	v_pk_add_f32 v[118:119], v[118:119], v[254:255]
	s_branch .Lres_e3a_done
.Lres_e3a_g7:
	s_nop 7
	v_lshlrev_b32_e32 v252, 16, v246
	v_and_b32_e32 v253, 0xffff0000, v246
	v_lshlrev_b32_e32 v254, 16, v247
	v_and_b32_e32 v255, 0xffff0000, v247
	v_lshlrev_b32_e32 v246, 16, v248
	v_and_b32_e32 v247, 0xffff0000, v248
	v_lshlrev_b32_e32 v248, 16, v249
	v_and_b32_e32 v249, 0xffff0000, v249
	v_pk_add_f32 v[252:253], v[252:253], v[246:247]
	v_pk_add_f32 v[254:255], v[254:255], v[248:249]
	v_pk_add_f32 v[76:77], v[76:77], v[252:253]
	v_pk_add_f32 v[78:79], v[78:79], v[254:255]
	s_branch .Lres_e3a_done
.Lres_e3a_g9:
	s_nop 7
	v_lshlrev_b32_e32 v252, 16, v246
	v_and_b32_e32 v253, 0xffff0000, v246
	v_lshlrev_b32_e32 v254, 16, v247
	v_and_b32_e32 v255, 0xffff0000, v247
	v_lshlrev_b32_e32 v246, 16, v248
	v_and_b32_e32 v247, 0xffff0000, v248
	v_lshlrev_b32_e32 v248, 16, v249
	v_and_b32_e32 v249, 0xffff0000, v249
	v_pk_add_f32 v[252:253], v[252:253], v[246:247]
	v_pk_add_f32 v[254:255], v[254:255], v[248:249]
	v_pk_add_f32 v[112:113], v[112:113], v[252:253]
	v_pk_add_f32 v[114:115], v[114:115], v[254:255]
	s_branch .Lres_e3a_done
.Lres_e3a_g11:
	s_nop 7
	v_lshlrev_b32_e32 v252, 16, v246
	v_and_b32_e32 v253, 0xffff0000, v246
	v_lshlrev_b32_e32 v254, 16, v247
	v_and_b32_e32 v255, 0xffff0000, v247
	v_lshlrev_b32_e32 v246, 16, v248
	v_and_b32_e32 v247, 0xffff0000, v248
	v_lshlrev_b32_e32 v248, 16, v249
	v_and_b32_e32 v249, 0xffff0000, v249
	v_pk_add_f32 v[252:253], v[252:253], v[246:247]
	v_pk_add_f32 v[254:255], v[254:255], v[248:249]
	v_pk_add_f32 v[72:73], v[72:73], v[252:253]
	v_pk_add_f32 v[74:75], v[74:75], v[254:255]
	s_branch .Lres_e3a_done
.Lres_e3a_g13:
	s_nop 7
	v_lshlrev_b32_e32 v252, 16, v246
	v_and_b32_e32 v253, 0xffff0000, v246
	v_lshlrev_b32_e32 v254, 16, v247
	v_and_b32_e32 v255, 0xffff0000, v247
	v_lshlrev_b32_e32 v246, 16, v248
	v_and_b32_e32 v247, 0xffff0000, v248
	v_lshlrev_b32_e32 v248, 16, v249
	v_and_b32_e32 v249, 0xffff0000, v249
	v_pk_add_f32 v[252:253], v[252:253], v[246:247]
	v_pk_add_f32 v[254:255], v[254:255], v[248:249]
	v_pk_add_f32 v[100:101], v[100:101], v[252:253]
	v_pk_add_f32 v[102:103], v[102:103], v[254:255]
	s_branch .Lres_e3a_done
.Lres_e3a_g15:
	s_nop 7
	v_lshlrev_b32_e32 v252, 16, v246
	v_and_b32_e32 v253, 0xffff0000, v246
	v_lshlrev_b32_e32 v254, 16, v247
	v_and_b32_e32 v255, 0xffff0000, v247
	v_lshlrev_b32_e32 v246, 16, v248
	v_and_b32_e32 v247, 0xffff0000, v248
	v_lshlrev_b32_e32 v248, 16, v249
	v_and_b32_e32 v249, 0xffff0000, v249
	v_pk_add_f32 v[252:253], v[252:253], v[246:247]
	v_pk_add_f32 v[254:255], v[254:255], v[248:249]
	v_pk_add_f32 v[68:69], v[68:69], v[252:253]
	v_pk_add_f32 v[70:71], v[70:71], v[254:255]
	s_branch .Lres_e3a_done
.Lres_e3a_done:
	s_add_i32 s10, s6, 1
	s_cmp_eq_u32 s10, 32
	s_cselect_b64 s[4:5], -1, 0
	s_and_b64 s[34:35], s[4:5], exec
	s_load_dwordx2 s[34:35], s[0:1], 0x110
	s_waitcnt lgkmcnt(0)
	s_barrier
	s_cselect_b32 s57, s34, 0
	s_add_i32 s57, s57, s7
	s_min_i32 s11, s57, s13
	s_cmpk_gt_i32 s11, 0x1ff
	s_mov_b64 s[6:7], -1
	s_cbranch_scc0 .LBB0_1796
	s_add_i32 s9, s11, 0xfffffe00
	s_mov_b64 s[6:7], 0

; #define MFMA16(a, b, c) __builtin_amdgcn_mfma_f32_16x16x32_bf16((a), (b), (c), 0, 0, 0)
;     ...
;     auto issue = [&](u32x4 (&ra)[4], u32x4 (&rb)[2], u32x4& rx) {
;       const int idc = l_id < last_id ? l_id : last_id;
;       int mt, nt; if (TMAP == 1) rem_tile(idc, mt, nt); else tile_of(idc, ntn, mt, nt);
;       const bf16_t* A = (l_kt < ktsplit) ? A0 : A1;
;       const int kk = (l_kt < ktsplit) ? l_kt : l_kt - ktsplit;
;       const int arow = mt * 2 * BMH + hh * BMH + srow;
;       const bf16_t* akb = A + kk * kstride + (tid & 7) * 8;
;       const bf16_t* wp = W + (size_t)(nt * 128 + wrow) * K + l_kt * 64 + (tid5 & 7) * 8;
; #pragma unroll
;       for (int i = 0; i < 4; ++i) {
;         int r = arow + 32 * i; r = r < M_ ? r : M_ - 1;
;         ra[i] = *(const u32x4*)(akb + (size_t)r * lda);
;       }
; #pragma unroll
;       for (int i = 0; i < 2; ++i) rb[i] = *(const u32x4*)(wp + (size_t)i * 64 * K);
;       if (TI == 5) rx = *(const u32x4*)(akb + (size_t)(arow - srow + 128) * lda);
;       if (++l_kt == nk) { l_kt = 0; l_id += G; }
;     };
;     ...
;     auto compute = [&](int buf) {
;       const unsigned char* Ab = As + buf * ASTG + (wn * 64 + lr) * 128;
;       const unsigned char* Ax = Ax0 + buf * 128;
;       const unsigned char* Bb = Bs + buf * 16384 + (wm * 64 + lr) * 128;
; #pragma unroll
;       for (int ks = 0; ks < 2; ++ks) {
;         if (TI == 5 && ks == 1) __builtin_amdgcn_sched_barrier(0);
;         const int sw = ((ks * 4 + lq) ^ (lr & 7)) << 4;
;         bf16x8 wf[4], xf[TI];
; #pragma unroll
;         for (int i = 0; i < 4; ++i) {
;           wf[i] = *(const bf16x8*)(Bb + i * 2048 + sw);
;           xf[i] = *(const bf16x8*)(Ab + i * 2048 + sw);
;         }
;         if (TI == 5) xf[TI - 1] = *(const bf16x8*)(Ax + ((ks * 4 + lq) << 4));
; #pragma unroll
;         for (int ni = 0; ni < 4; ++ni)
; #pragma unroll
;           for (int ti = 0; ti < 4; ++ti) acc[ni][ti] = MFMA16(wf[ni], xf[ti], acc[ni][ti]);
;         if (TI == 5) {
;           if (wn == 0) { acc[0][TI - 1] = MFMA16(wf[0], xf[TI - 1], acc[0][TI - 1]); acc[1][TI - 1] = MFMA16(wf[1], xf[TI - 1], acc[1][TI - 1]); }
;           else { acc[2][TI - 1] = MFMA16(wf[2], xf[TI - 1], acc[2][TI - 1]); acc[3][TI - 1] = MFMA16(wf[3], xf[TI - 1], acc[3][TI - 1]); }
;         }
;       }
.LBB0_1798:
	s_and_b64 s[4:5], s[4:5], exec
	s_cselect_b32 s58, 0, s10
	s_cmp_lt_i32 s58, 16
	s_cselect_b32 s4, 0, -16
	s_cselect_b32 s7, s47, s55
	s_cselect_b32 s10, s46, s54
	s_add_i32 s4, s4, s58
	s_lshl_b32 s4, s4, 6
	ds_read_b128 v[148:151], v13 offset:49152
	ds_read_b128 v[24:27], v15 offset:16384
	s_ashr_i32 s5, s4, 31
	v_add_u32_e32 v210, s6, v176
	s_lshl_b64 s[4:5], s[4:5], 1
	s_add_u32 s4, s10, s4
	v_min_i32_e32 v2, 0x405f, v210
	s_addc_u32 s5, s7, s5
	v_mov_b32_e32 v169, v12
	ds_read_b128 v[152:155], v13 offset:51200
	s_waitcnt vmcnt(9)
	ds_read_b128 v[32:35], v15 offset:18432
	ds_read_b128 v[160:163], v15 offset:20480
	ds_read_b128 v[204:207], v15 offset:22528
	v_ashrrev_i32_e32 v3, 31, v2
	v_lshl_add_u64 v[208:209], s[4:5], 0, v[168:169]
	v_min_i32_e32 v0, 0x407f, v210
	v_lshlrev_b64 v[2:3], 11, v[2:3]
	v_ashrrev_i32_e32 v1, 31, v0
	v_lshl_add_u64 v[2:3], v[208:209], 0, v[2:3]
	v_lshlrev_b64 v[0:1], 11, v[0:1]
	v_add_co_u32_e32 v4, vcc, s82, v2
	v_lshl_add_u64 v[0:1], v[208:209], 0, v[0:1]
	s_nop 0
	v_addc_co_u32_e32 v5, vcc, 0, v3, vcc
	s_waitcnt lgkmcnt(1)
	v_mfma_f32_16x16x32_bf16 v[140:143], v[148:151], v[160:163], v[132:135]
	global_load_dwordx4 v[0:3], v[0:1], off
	s_nop 0
	global_load_dwordx4 v[4:7], v[4:5], off
	ds_read_b128 v[132:135], v13 offset:53248
	ds_read_b128 v[156:159], v13 offset:55296
	v_min_i32_e32 v16, 0x403f, v210
	v_ashrrev_i32_e32 v17, 31, v16
	v_lshl_add_u32 v28, s9, 7, v174
	v_lshlrev_b64 v[16:17], 11, v[16:17]
	v_min_i32_e32 v18, 0x401f, v210
	v_ashrrev_i32_e32 v29, 31, v28
	v_lshl_add_u64 v[16:17], v[208:209], 0, v[16:17]
	v_ashrrev_i32_e32 v19, 31, v18
	s_lshl_b32 s4, s58, 6
	v_add_co_u32_e32 v16, vcc, s2, v16
	v_lshlrev_b64 v[18:19], 11, v[18:19]
	v_lshlrev_b64 v[28:29], 12, v[28:29]
	s_ashr_i32 s5, s4, 31
	v_addc_co_u32_e32 v17, vcc, 0, v17, vcc
	v_lshl_add_u64 v[18:19], v[208:209], 0, v[18:19]
	s_mov_b32 s3, 0x30000
	v_lshl_add_u64 v[28:29], s[48:49], 0, v[28:29]
	v_sub_u32_e32 v13, v210, v173
	s_waitcnt lgkmcnt(1)
	v_mfma_f32_16x16x32_bf16 v[144:147], v[132:135], v[24:27], v[104:107]
	v_add_co_u32_e32 v20, vcc, s3, v18
	v_lshl_add_u64 v[28:29], s[4:5], 1, v[28:29]
	v_mov_b32_e32 v171, v12
	v_add_u32_e32 v104, 0x80, v13
	v_addc_co_u32_e32 v21, vcc, 0, v19, vcc
	v_lshl_add_u64 v[28:29], v[28:29], 0, v[170:171]
	s_mov_b32 s3, 0x40000
	v_ashrrev_i32_e32 v105, 31, v104
	v_mfma_f32_16x16x32_bf16 v[128:131], v[148:151], v[32:35], v[128:131]
	v_add_co_u32_e32 v30, vcc, s3, v28
	global_load_dwordx4 v[16:19], v[16:17], off
	s_nop 0
	global_load_dwordx4 v[20:23], v[20:21], off
	v_mfma_f32_16x16x32_bf16 v[116:119], v[152:155], v[32:35], v[116:119]
	v_addc_co_u32_e32 v31, vcc, 0, v29, vcc
	v_mfma_f32_16x16x32_bf16 v[96:99], v[132:135], v[32:35], v[96:99]
	s_waitcnt lgkmcnt(0)
	v_mfma_f32_16x16x32_bf16 v[76:79], v[156:159], v[32:35], v[76:79]
	v_lshlrev_b64 v[32:33], 11, v[104:105]
	v_lshl_add_u64 v[32:33], v[208:209], 0, v[32:33]
	v_mfma_f32_16x16x32_bf16 v[136:139], v[148:151], v[24:27], v[136:139]
	v_mfma_f32_16x16x32_bf16 v[120:123], v[152:155], v[24:27], v[120:123]
	v_mfma_f32_16x16x32_bf16 v[80:83], v[156:159], v[24:27], v[80:83]
	global_load_dwordx4 v[24:27], v[28:29], off
	s_nop 0
	global_load_dwordx4 v[28:31], v[30:31], off
	ds_read_b128 v[104:107], v185 offset:128
	global_load_dwordx4 v[32:35], v[32:33], off
	s_lshr_b32 s101, s8, 2
	s_mulk_i32 s101, 0x7f80
	v_add_u32_e32 v250, s100, v251
	v_add_u32_e32 v250, s101, v250
	s_lshl_b32 s101, s8, 5
	v_add_u32_e32 v250, s101, v250
	s_cmp_lt_u32 s8, 15
	s_cselect_b32 s101, -1, 0
	v_and_b32_e32 v250, s101, v250
	global_load_dwordx2 v[246:247], v250, s[44:45] offset:32
	global_load_dwordx2 v[248:249], v250, s[50:51] offset:32
	v_mfma_f32_16x16x32_bf16 v[124:127], v[148:151], v[204:207], v[124:127]
	v_mfma_f32_16x16x32_bf16 v[112:115], v[152:155], v[160:163], v[112:115]
	v_mfma_f32_16x16x32_bf16 v[100:103], v[152:155], v[204:207], v[100:103]
	v_mfma_f32_16x16x32_bf16 v[92:95], v[132:135], v[160:163], v[92:95]
	v_mfma_f32_16x16x32_bf16 v[84:87], v[132:135], v[204:207], v[84:87]
	v_mfma_f32_16x16x32_bf16 v[72:75], v[156:159], v[160:163], v[72:75]
	v_mfma_f32_16x16x32_bf16 v[68:71], v[156:159], v[204:207], v[68:71]
	s_and_saveexec_b64 s[4:5], s[40:41]
	s_xor_b64 s[4:5], exec, s[4:5]
	s_cbranch_execz .LBB0_1800
	s_waitcnt lgkmcnt(0)
	v_mfma_f32_16x16x32_bf16 v[36:39], v[132:135], v[104:107], v[36:39]
	v_mfma_f32_16x16x32_bf16 v[8:11], v[156:159], v[104:107], v[8:11]

; __device__ __forceinline__ float bflo(unsigned v) { return __uint_as_float(v << 16); }
; __device__ __forceinline__ float bfhi(unsigned v) { return __uint_as_float(v & 0xffff0000u); }
; template <int EPI, int TI>
; __device__ __forceinline__ void gemm_epilogue(const WS& ws, const f32x4 (&acc)[4][TI], const float (&rs)[TI], int tok0, int n0,
;                                               int wm, int wn, int lr, int lq, bool dry) {
;     ...
;   } else {
; #pragma unroll
;     for (int ni = 0; ni < 4; ++ni)
; #pragma unroll
;       for (int ti = 0; ti < TI; ++ti) {
;         if (!(ti < 4 || (lr == 0 && (ni >> 1) == wn))) continue;
;         const size_t off = (size_t)(ti < 4 ? tokr(ti) : tok0 + 128) * 1024 + nw + ni * 16 + 4 * lq;
;         const u32x2 hi = *(const u32x2*)(ws.HHI + off), lo = *(const u32x2*)(ws.HLO + off);
;         const float h0 = bflo(hi.x) + bflo(lo.x) + acc[ni][ti][0], h1 = bfhi(hi.x) + bfhi(lo.x) + acc[ni][ti][1];
;         const float h2 = bflo(hi.y) + bflo(lo.y) + acc[ni][ti][2], h3 = bfhi(hi.y) + bfhi(lo.y) + acc[ni][ti][3];
;         u32x2 nh; nh.x = cvt_pk_bf16(h0, h1); nh.y = cvt_pk_bf16(h2, h3);
;         u32x2 nl; nl.x = cvt_pk_bf16(h0 - bflo(nh.x), h1 - bfhi(nh.x)); nl.y = cvt_pk_bf16(h2 - bflo(nh.y), h3 - bfhi(nh.y));
;         if (!dry) { *(u32x2*)(ws.HHI + off) = nh; *(u32x2*)(ws.HLO + off) = nl; }
;       }
.LBB0_1812:
	s_waitcnt lgkmcnt(0)
	s_waitcnt vmcnt(0)
	v_mbcnt_lo_u32_b32 v13, -1, 0
	v_mbcnt_hi_u32_b32 v13, -1, v13
	s_add_i32 s5, s4, 0x80
	v_and_b32_e32 v14, 3, v13
	v_lshrrev_b32_e32 v13, 2, v13
	s_lshl_b32 s5, s5, 11
	v_lshl_add_u32 v15, v14, 4, v13
	v_and_b32_e32 v247, 64, v184
	v_lshlrev_b32_e32 v15, 2, v15
	v_add3_u32 v13, s4, v247, v13
	v_lshl_add_u32 v247, s6, 7, v183
	s_mov_b64 s[6:7], exec
	v_lshl_add_u32 v14, v14, 2, v247
	v_or_b32_e32 v247, v247, v172
	v_lshlrev_b32_e32 v14, 1, v14
	v_lshlrev_b32_e32 v247, 1, v247
	v_lshl_add_u32 v242, v13, 11, v14
	v_add_u32_e32 v246, s5, v247
	v_add_u32_e32 v243, 0x8000, v242
	v_add_u32_e32 v244, 0x10000, v242
	v_add_u32_e32 v245, 0x18000, v242
	s_and_b64 exec, s[6:7], s[42:43]
	global_load_dwordx2 v[204:205], v246, s[44:45]
	global_load_dwordx2 v[206:207], v246, s[50:51]
	global_load_dwordx2 v[208:209], v246, s[44:45] offset:32
	global_load_dwordx2 v[210:211], v246, s[50:51] offset:32
	s_and_b64 exec, s[6:7], s[52:53]
	global_load_dwordx2 v[212:213], v246, s[44:45] offset:64
	global_load_dwordx2 v[214:215], v246, s[50:51] offset:64
	global_load_dwordx2 v[216:217], v246, s[44:45] offset:96
	global_load_dwordx2 v[218:219], v246, s[50:51] offset:96
	s_mov_b64 exec, s[6:7]
	ds_bpermute_b32 v136, v15, v136
	ds_bpermute_b32 v137, v15, v137
	ds_bpermute_b32 v138, v15, v138
	ds_bpermute_b32 v139, v15, v139
	ds_bpermute_b32 v120, v15, v120
	ds_bpermute_b32 v121, v15, v121
	ds_bpermute_b32 v122, v15, v122
	ds_bpermute_b32 v123, v15, v123
	ds_bpermute_b32 v100, v15, v100
	ds_bpermute_b32 v101, v15, v101
	ds_bpermute_b32 v102, v15, v102
	ds_bpermute_b32 v103, v15, v103
	s_waitcnt lgkmcnt(8)
	v_cvt_pk_bf16_f32 v140, v136, v137
	v_cvt_pk_bf16_f32 v141, v138, v139
	v_lshlrev_b32_e32 v252, 16, v140
	v_and_b32_e32 v253, 0xffff0000, v140
	v_lshlrev_b32_e32 v254, 16, v141
	v_and_b32_e32 v255, 0xffff0000, v141
	v_pk_add_f32 v[136:137], v[136:137], v[252:253] neg_lo:[0,1] neg_hi:[0,1]
	v_pk_add_f32 v[138:139], v[138:139], v[254:255] neg_lo:[0,1] neg_hi:[0,1]
	v_cvt_pk_bf16_f32 v142, v136, v137
	v_cvt_pk_bf16_f32 v143, v138, v139
	global_store_dwordx2 v242, v[140:141], s[44:45]
	global_store_dwordx2 v242, v[142:143], s[50:51]
	ds_bpermute_b32 v80, v15, v80
	ds_bpermute_b32 v81, v15, v81
	ds_bpermute_b32 v82, v15, v82
	ds_bpermute_b32 v83, v15, v83
	s_waitcnt lgkmcnt(8)
	v_cvt_pk_bf16_f32 v144, v120, v121
	v_cvt_pk_bf16_f32 v145, v122, v123
	v_lshlrev_b32_e32 v252, 16, v144
	v_and_b32_e32 v253, 0xffff0000, v144
	v_lshlrev_b32_e32 v254, 16, v145
	v_and_b32_e32 v255, 0xffff0000, v145
	v_pk_add_f32 v[120:121], v[120:121], v[252:253] neg_lo:[0,1] neg_hi:[0,1]
	v_pk_add_f32 v[122:123], v[122:123], v[254:255] neg_lo:[0,1] neg_hi:[0,1]
	v_cvt_pk_bf16_f32 v146, v120, v121
	v_cvt_pk_bf16_f32 v147, v122, v123
	global_store_dwordx2 v242, v[144:145], s[44:45] offset:32
	global_store_dwordx2 v242, v[146:147], s[50:51] offset:32
	ds_bpermute_b32 v132, v15, v132
	ds_bpermute_b32 v133, v15, v133
	ds_bpermute_b32 v134, v15, v134
	ds_bpermute_b32 v135, v15, v135
	s_waitcnt lgkmcnt(8)
	v_cvt_pk_bf16_f32 v148, v100, v101
	v_cvt_pk_bf16_f32 v149, v102, v103
	v_lshlrev_b32_e32 v252, 16, v148
	v_and_b32_e32 v253, 0xffff0000, v148
	v_lshlrev_b32_e32 v254, 16, v149
	v_and_b32_e32 v255, 0xffff0000, v149
	v_pk_add_f32 v[100:101], v[100:101], v[252:253] neg_lo:[0,1] neg_hi:[0,1]
	v_pk_add_f32 v[102:103], v[102:103], v[254:255] neg_lo:[0,1] neg_hi:[0,1]
	v_cvt_pk_bf16_f32 v150, v100, v101
	v_cvt_pk_bf16_f32 v151, v102, v103
	global_store_dwordx2 v242, v[148:149], s[44:45] offset:64
	global_store_dwordx2 v242, v[150:151], s[50:51] offset:64
	ds_bpermute_b32 v116, v15, v116
	ds_bpermute_b32 v117, v15, v117
	ds_bpermute_b32 v118, v15, v118
	ds_bpermute_b32 v119, v15, v119
	s_waitcnt lgkmcnt(8)
	v_cvt_pk_bf16_f32 v152, v80, v81
	v_cvt_pk_bf16_f32 v153, v82, v83
	v_lshlrev_b32_e32 v252, 16, v152
	v_and_b32_e32 v253, 0xffff0000, v152
	v_lshlrev_b32_e32 v254, 16, v153
	v_and_b32_e32 v255, 0xffff0000, v153
	v_pk_add_f32 v[80:81], v[80:81], v[252:253] neg_lo:[0,1] neg_hi:[0,1]
	v_pk_add_f32 v[82:83], v[82:83], v[254:255] neg_lo:[0,1] neg_hi:[0,1]
	v_cvt_pk_bf16_f32 v154, v80, v81
	v_cvt_pk_bf16_f32 v155, v82, v83
	global_store_dwordx2 v242, v[152:153], s[44:45] offset:96
	global_store_dwordx2 v242, v[154:155], s[50:51] offset:96
	ds_bpermute_b32 v96, v15, v96
	ds_bpermute_b32 v97, v15, v97
	ds_bpermute_b32 v98, v15, v98
	ds_bpermute_b32 v99, v15, v99
	s_waitcnt lgkmcnt(8)
	v_cvt_pk_bf16_f32 v156, v132, v133
	v_cvt_pk_bf16_f32 v157, v134, v135
	v_lshlrev_b32_e32 v252, 16, v156
	v_and_b32_e32 v253, 0xffff0000, v156
	v_lshlrev_b32_e32 v254, 16, v157
	v_and_b32_e32 v255, 0xffff0000, v157
	v_pk_add_f32 v[132:133], v[132:133], v[252:253] neg_lo:[0,1] neg_hi:[0,1]
	v_pk_add_f32 v[134:135], v[134:135], v[254:255] neg_lo:[0,1] neg_hi:[0,1]
	v_cvt_pk_bf16_f32 v158, v132, v133
	v_cvt_pk_bf16_f32 v159, v134, v135
	global_store_dwordx2 v243, v[156:157], s[44:45]
	global_store_dwordx2 v243, v[158:159], s[50:51]
	ds_bpermute_b32 v76, v15, v76
	ds_bpermute_b32 v77, v15, v77
	ds_bpermute_b32 v78, v15, v78
	ds_bpermute_b32 v79, v15, v79
	s_waitcnt lgkmcnt(8)
	v_cvt_pk_bf16_f32 v140, v116, v117
	v_cvt_pk_bf16_f32 v141, v118, v119
	v_lshlrev_b32_e32 v252, 16, v140
	v_and_b32_e32 v253, 0xffff0000, v140
	v_lshlrev_b32_e32 v254, 16, v141
	v_and_b32_e32 v255, 0xffff0000, v141
	v_pk_add_f32 v[116:117], v[116:117], v[252:253] neg_lo:[0,1] neg_hi:[0,1]
	v_pk_add_f32 v[118:119], v[118:119], v[254:255] neg_lo:[0,1] neg_hi:[0,1]
	v_cvt_pk_bf16_f32 v142, v116, v117
	v_cvt_pk_bf16_f32 v143, v118, v119
	global_store_dwordx2 v243, v[140:141], s[44:45] offset:32
	global_store_dwordx2 v243, v[142:143], s[50:51] offset:32
	ds_bpermute_b32 v128, v15, v128
	ds_bpermute_b32 v129, v15, v129
	ds_bpermute_b32 v130, v15, v130
	ds_bpermute_b32 v131, v15, v131
	s_waitcnt lgkmcnt(8)
; __device__ __forceinline__ float bflo(unsigned v) { return __uint_as_float(v << 16); }
; __device__ __forceinline__ float bfhi(unsigned v) { return __uint_as_float(v & 0xffff0000u); }
; template <int EPI, int TI>
; __device__ __forceinline__ void gemm_epilogue(const WS& ws, const f32x4 (&acc)[4][TI], const float (&rs)[TI], int tok0, int n0,
;                                               int wm, int wn, int lr, int lq, bool dry) {
;     ...
;   } else {
; #pragma unroll
;     for (int ni = 0; ni < 4; ++ni)
; #pragma unroll
;       for (int ti = 0; ti < TI; ++ti) {
;         if (!(ti < 4 || (lr == 0 && (ni >> 1) == wn))) continue;
;         const size_t off = (size_t)(ti < 4 ? tokr(ti) : tok0 + 128) * 1024 + nw + ni * 16 + 4 * lq;
;         const u32x2 hi = *(const u32x2*)(ws.HHI + off), lo = *(const u32x2*)(ws.HLO + off);
;         const float h0 = bflo(hi.x) + bflo(lo.x) + acc[ni][ti][0], h1 = bfhi(hi.x) + bfhi(lo.x) + acc[ni][ti][1];
;         const float h2 = bflo(hi.y) + bflo(lo.y) + acc[ni][ti][2], h3 = bfhi(hi.y) + bfhi(lo.y) + acc[ni][ti][3];
;         u32x2 nh; nh.x = cvt_pk_bf16(h0, h1); nh.y = cvt_pk_bf16(h2, h3);
;         u32x2 nl; nl.x = cvt_pk_bf16(h0 - bflo(nh.x), h1 - bfhi(nh.x)); nl.y = cvt_pk_bf16(h2 - bflo(nh.y), h3 - bfhi(nh.y));
;         if (!dry) { *(u32x2*)(ws.HHI + off) = nh; *(u32x2*)(ws.HLO + off) = nl; }
;       }
	v_cvt_pk_bf16_f32 v144, v96, v97
	v_cvt_pk_bf16_f32 v145, v98, v99
	v_lshlrev_b32_e32 v252, 16, v144
	v_and_b32_e32 v253, 0xffff0000, v144
	v_lshlrev_b32_e32 v254, 16, v145
	v_and_b32_e32 v255, 0xffff0000, v145
	v_pk_add_f32 v[96:97], v[96:97], v[252:253] neg_lo:[0,1] neg_hi:[0,1]
	v_pk_add_f32 v[98:99], v[98:99], v[254:255] neg_lo:[0,1] neg_hi:[0,1]
	v_cvt_pk_bf16_f32 v146, v96, v97
	v_cvt_pk_bf16_f32 v147, v98, v99
	global_store_dwordx2 v243, v[144:145], s[44:45] offset:64
	global_store_dwordx2 v243, v[146:147], s[50:51] offset:64
	ds_bpermute_b32 v112, v15, v112
	ds_bpermute_b32 v113, v15, v113
	ds_bpermute_b32 v114, v15, v114
	ds_bpermute_b32 v115, v15, v115
	s_waitcnt lgkmcnt(8)
	v_cvt_pk_bf16_f32 v148, v76, v77
	v_cvt_pk_bf16_f32 v149, v78, v79
	v_lshlrev_b32_e32 v252, 16, v148
	v_and_b32_e32 v253, 0xffff0000, v148
	v_lshlrev_b32_e32 v254, 16, v149
	v_and_b32_e32 v255, 0xffff0000, v149
	v_pk_add_f32 v[76:77], v[76:77], v[252:253] neg_lo:[0,1] neg_hi:[0,1]
	v_pk_add_f32 v[78:79], v[78:79], v[254:255] neg_lo:[0,1] neg_hi:[0,1]
	v_cvt_pk_bf16_f32 v150, v76, v77
	v_cvt_pk_bf16_f32 v151, v78, v79
	global_store_dwordx2 v243, v[148:149], s[44:45] offset:96
	global_store_dwordx2 v243, v[150:151], s[50:51] offset:96
	ds_bpermute_b32 v92, v15, v92
	ds_bpermute_b32 v93, v15, v93
	ds_bpermute_b32 v94, v15, v94
	ds_bpermute_b32 v95, v15, v95
	s_waitcnt lgkmcnt(8)
	v_cvt_pk_bf16_f32 v152, v128, v129
	v_cvt_pk_bf16_f32 v153, v130, v131
	v_lshlrev_b32_e32 v252, 16, v152
	v_and_b32_e32 v253, 0xffff0000, v152
	v_lshlrev_b32_e32 v254, 16, v153
	v_and_b32_e32 v255, 0xffff0000, v153
	v_pk_add_f32 v[128:129], v[128:129], v[252:253] neg_lo:[0,1] neg_hi:[0,1]
	v_pk_add_f32 v[130:131], v[130:131], v[254:255] neg_lo:[0,1] neg_hi:[0,1]
	v_cvt_pk_bf16_f32 v154, v128, v129
	v_cvt_pk_bf16_f32 v155, v130, v131
	global_store_dwordx2 v244, v[152:153], s[44:45]
	global_store_dwordx2 v244, v[154:155], s[50:51]
	ds_bpermute_b32 v72, v15, v72
	ds_bpermute_b32 v73, v15, v73
	ds_bpermute_b32 v74, v15, v74
	ds_bpermute_b32 v75, v15, v75
	s_waitcnt lgkmcnt(8)
	v_cvt_pk_bf16_f32 v156, v112, v113
	v_cvt_pk_bf16_f32 v157, v114, v115
	v_lshlrev_b32_e32 v252, 16, v156
	v_and_b32_e32 v253, 0xffff0000, v156
	v_lshlrev_b32_e32 v254, 16, v157
	v_and_b32_e32 v255, 0xffff0000, v157
	v_pk_add_f32 v[112:113], v[112:113], v[252:253] neg_lo:[0,1] neg_hi:[0,1]
	v_pk_add_f32 v[114:115], v[114:115], v[254:255] neg_lo:[0,1] neg_hi:[0,1]
	v_cvt_pk_bf16_f32 v158, v112, v113
	v_cvt_pk_bf16_f32 v159, v114, v115
	global_store_dwordx2 v244, v[156:157], s[44:45] offset:32
	global_store_dwordx2 v244, v[158:159], s[50:51] offset:32
	ds_bpermute_b32 v124, v15, v124
	ds_bpermute_b32 v125, v15, v125
	ds_bpermute_b32 v126, v15, v126
	ds_bpermute_b32 v127, v15, v127
	s_waitcnt lgkmcnt(8)
	v_cvt_pk_bf16_f32 v140, v92, v93
	v_cvt_pk_bf16_f32 v141, v94, v95
	v_lshlrev_b32_e32 v252, 16, v140
	v_and_b32_e32 v253, 0xffff0000, v140
	v_lshlrev_b32_e32 v254, 16, v141
	v_and_b32_e32 v255, 0xffff0000, v141
	v_pk_add_f32 v[92:93], v[92:93], v[252:253] neg_lo:[0,1] neg_hi:[0,1]
	v_pk_add_f32 v[94:95], v[94:95], v[254:255] neg_lo:[0,1] neg_hi:[0,1]
	v_cvt_pk_bf16_f32 v142, v92, v93
	v_cvt_pk_bf16_f32 v143, v94, v95
	global_store_dwordx2 v244, v[140:141], s[44:45] offset:64
	global_store_dwordx2 v244, v[142:143], s[50:51] offset:64
	ds_bpermute_b32 v104, v15, v104
	ds_bpermute_b32 v105, v15, v105
	ds_bpermute_b32 v106, v15, v106
	ds_bpermute_b32 v107, v15, v107
	s_waitcnt lgkmcnt(8)
	v_cvt_pk_bf16_f32 v144, v72, v73
	v_cvt_pk_bf16_f32 v145, v74, v75
	v_lshlrev_b32_e32 v252, 16, v144
	v_and_b32_e32 v253, 0xffff0000, v144
	v_lshlrev_b32_e32 v254, 16, v145
	v_and_b32_e32 v255, 0xffff0000, v145
	v_pk_add_f32 v[72:73], v[72:73], v[252:253] neg_lo:[0,1] neg_hi:[0,1]
	v_pk_add_f32 v[74:75], v[74:75], v[254:255] neg_lo:[0,1] neg_hi:[0,1]
	v_cvt_pk_bf16_f32 v146, v72, v73
	v_cvt_pk_bf16_f32 v147, v74, v75
	global_store_dwordx2 v244, v[144:145], s[44:45] offset:96
	global_store_dwordx2 v244, v[146:147], s[50:51] offset:96
	ds_bpermute_b32 v84, v15, v84
	ds_bpermute_b32 v85, v15, v85
	ds_bpermute_b32 v86, v15, v86
	ds_bpermute_b32 v87, v15, v87
	s_waitcnt lgkmcnt(8)
	v_cvt_pk_bf16_f32 v148, v124, v125
	v_cvt_pk_bf16_f32 v149, v126, v127
	v_lshlrev_b32_e32 v252, 16, v148
	v_and_b32_e32 v253, 0xffff0000, v148
	v_lshlrev_b32_e32 v254, 16, v149
	v_and_b32_e32 v255, 0xffff0000, v149
	v_pk_add_f32 v[124:125], v[124:125], v[252:253] neg_lo:[0,1] neg_hi:[0,1]
	v_pk_add_f32 v[126:127], v[126:127], v[254:255] neg_lo:[0,1] neg_hi:[0,1]
	v_cvt_pk_bf16_f32 v150, v124, v125
	v_cvt_pk_bf16_f32 v151, v126, v127
	global_store_dwordx2 v245, v[148:149], s[44:45]
	global_store_dwordx2 v245, v[150:151], s[50:51]
	ds_bpermute_b32 v68, v15, v68
	ds_bpermute_b32 v69, v15, v69
	ds_bpermute_b32 v70, v15, v70
	ds_bpermute_b32 v71, v15, v71
	s_waitcnt lgkmcnt(8)
	v_cvt_pk_bf16_f32 v152, v104, v105
	v_cvt_pk_bf16_f32 v153, v106, v107
	v_lshlrev_b32_e32 v252, 16, v152
	v_and_b32_e32 v253, 0xffff0000, v152
	v_lshlrev_b32_e32 v254, 16, v153
	v_and_b32_e32 v255, 0xffff0000, v153
	v_pk_add_f32 v[104:105], v[104:105], v[252:253] neg_lo:[0,1] neg_hi:[0,1]
	v_pk_add_f32 v[106:107], v[106:107], v[254:255] neg_lo:[0,1] neg_hi:[0,1]
	v_cvt_pk_bf16_f32 v154, v104, v105
	v_cvt_pk_bf16_f32 v155, v106, v107
	global_store_dwordx2 v245, v[152:153], s[44:45] offset:32
	global_store_dwordx2 v245, v[154:155], s[50:51] offset:32
	s_waitcnt lgkmcnt(4)
; __device__ __forceinline__ float bflo(unsigned v) { return __uint_as_float(v << 16); }
; __device__ __forceinline__ float bfhi(unsigned v) { return __uint_as_float(v & 0xffff0000u); }
; template <int EPI, int TI>
; __device__ __forceinline__ void gemm_epilogue(const WS& ws, const f32x4 (&acc)[4][TI], const float (&rs)[TI], int tok0, int n0,
;                                               int wm, int wn, int lr, int lq, bool dry) {
;     ...
;   } else {
; #pragma unroll
;     for (int ni = 0; ni < 4; ++ni)
; #pragma unroll
;       for (int ti = 0; ti < TI; ++ti) {
;         if (!(ti < 4 || (lr == 0 && (ni >> 1) == wn))) continue;
;         const size_t off = (size_t)(ti < 4 ? tokr(ti) : tok0 + 128) * 1024 + nw + ni * 16 + 4 * lq;
;         const u32x2 hi = *(const u32x2*)(ws.HHI + off), lo = *(const u32x2*)(ws.HLO + off);
;         const float h0 = bflo(hi.x) + bflo(lo.x) + acc[ni][ti][0], h1 = bfhi(hi.x) + bfhi(lo.x) + acc[ni][ti][1];
;         const float h2 = bflo(hi.y) + bflo(lo.y) + acc[ni][ti][2], h3 = bfhi(hi.y) + bfhi(lo.y) + acc[ni][ti][3];
;         u32x2 nh; nh.x = cvt_pk_bf16(h0, h1); nh.y = cvt_pk_bf16(h2, h3);
;         u32x2 nl; nl.x = cvt_pk_bf16(h0 - bflo(nh.x), h1 - bfhi(nh.x)); nl.y = cvt_pk_bf16(h2 - bflo(nh.y), h3 - bfhi(nh.y));
;         if (!dry) { *(u32x2*)(ws.HHI + off) = nh; *(u32x2*)(ws.HLO + off) = nl; }
;       }
	v_cvt_pk_bf16_f32 v156, v84, v85
	v_cvt_pk_bf16_f32 v157, v86, v87
	v_lshlrev_b32_e32 v252, 16, v156
	v_and_b32_e32 v253, 0xffff0000, v156
	v_lshlrev_b32_e32 v254, 16, v157
	v_and_b32_e32 v255, 0xffff0000, v157
	v_pk_add_f32 v[84:85], v[84:85], v[252:253] neg_lo:[0,1] neg_hi:[0,1]
	v_pk_add_f32 v[86:87], v[86:87], v[254:255] neg_lo:[0,1] neg_hi:[0,1]
	v_cvt_pk_bf16_f32 v158, v84, v85
	v_cvt_pk_bf16_f32 v159, v86, v87
	global_store_dwordx2 v245, v[156:157], s[44:45] offset:64
	global_store_dwordx2 v245, v[158:159], s[50:51] offset:64
	s_waitcnt lgkmcnt(0)
	v_cvt_pk_bf16_f32 v140, v68, v69
	v_cvt_pk_bf16_f32 v141, v70, v71
	v_lshlrev_b32_e32 v252, 16, v140
	v_and_b32_e32 v253, 0xffff0000, v140
	v_lshlrev_b32_e32 v254, 16, v141
	v_and_b32_e32 v255, 0xffff0000, v141
	v_pk_add_f32 v[68:69], v[68:69], v[252:253] neg_lo:[0,1] neg_hi:[0,1]
	v_pk_add_f32 v[70:71], v[70:71], v[254:255] neg_lo:[0,1] neg_hi:[0,1]
	v_cvt_pk_bf16_f32 v142, v68, v69
	v_cvt_pk_bf16_f32 v143, v70, v71
	global_store_dwordx2 v245, v[140:141], s[44:45] offset:96
	global_store_dwordx2 v245, v[142:143], s[50:51] offset:96
	s_and_b64 exec, s[6:7], s[42:43]
	s_waitcnt vmcnt(38)
	v_lshlrev_b32_e32 v252, 16, v204
	v_and_b32_e32 v253, 0xffff0000, v204
	v_lshlrev_b32_e32 v160, 16, v206
	v_and_b32_e32 v161, 0xffff0000, v206
	v_lshlrev_b32_e32 v254, 16, v205
	v_and_b32_e32 v255, 0xffff0000, v205
	v_lshlrev_b32_e32 v162, 16, v207
	v_and_b32_e32 v163, 0xffff0000, v207
	v_pk_add_f32 v[252:253], v[252:253], v[160:161]
	v_pk_add_f32 v[254:255], v[254:255], v[162:163]
	v_pk_add_f32 v[108:109], v[108:109], v[252:253]
	v_pk_add_f32 v[110:111], v[110:111], v[254:255]
	v_cvt_pk_bf16_f32 v204, v108, v109
	v_cvt_pk_bf16_f32 v205, v110, v111
	v_lshlrev_b32_e32 v252, 16, v204
	v_and_b32_e32 v253, 0xffff0000, v204
	v_lshlrev_b32_e32 v254, 16, v205
	v_and_b32_e32 v255, 0xffff0000, v205
	v_pk_add_f32 v[108:109], v[108:109], v[252:253] neg_lo:[0,1] neg_hi:[0,1]
	v_pk_add_f32 v[110:111], v[110:111], v[254:255] neg_lo:[0,1] neg_hi:[0,1]
	v_cvt_pk_bf16_f32 v206, v108, v109
	v_cvt_pk_bf16_f32 v207, v110, v111
	global_store_dwordx2 v246, v[204:205], s[44:45]
	global_store_dwordx2 v246, v[206:207], s[50:51]
	s_waitcnt vmcnt(38)
	v_lshlrev_b32_e32 v252, 16, v208
	v_and_b32_e32 v253, 0xffff0000, v208
	v_lshlrev_b32_e32 v160, 16, v210
	v_and_b32_e32 v161, 0xffff0000, v210
	v_lshlrev_b32_e32 v254, 16, v209
	v_and_b32_e32 v255, 0xffff0000, v209
	v_lshlrev_b32_e32 v162, 16, v211
	v_and_b32_e32 v163, 0xffff0000, v211
	v_pk_add_f32 v[252:253], v[252:253], v[160:161]
	v_pk_add_f32 v[254:255], v[254:255], v[162:163]
	v_pk_add_f32 v[88:89], v[88:89], v[252:253]
	v_pk_add_f32 v[90:91], v[90:91], v[254:255]
	v_cvt_pk_bf16_f32 v208, v88, v89
	v_cvt_pk_bf16_f32 v209, v90, v91
	v_lshlrev_b32_e32 v252, 16, v208
	v_and_b32_e32 v253, 0xffff0000, v208
	v_lshlrev_b32_e32 v254, 16, v209
	v_and_b32_e32 v255, 0xffff0000, v209
	v_pk_add_f32 v[88:89], v[88:89], v[252:253] neg_lo:[0,1] neg_hi:[0,1]
	v_pk_add_f32 v[90:91], v[90:91], v[254:255] neg_lo:[0,1] neg_hi:[0,1]
	v_cvt_pk_bf16_f32 v210, v88, v89
	v_cvt_pk_bf16_f32 v211, v90, v91
	global_store_dwordx2 v246, v[208:209], s[44:45] offset:32
	global_store_dwordx2 v246, v[210:211], s[50:51] offset:32
	s_and_b64 exec, s[6:7], s[52:53]
	s_waitcnt vmcnt(38)
	v_lshlrev_b32_e32 v252, 16, v212
	v_and_b32_e32 v253, 0xffff0000, v212
	v_lshlrev_b32_e32 v160, 16, v214
	v_and_b32_e32 v161, 0xffff0000, v214
	v_lshlrev_b32_e32 v254, 16, v213
	v_and_b32_e32 v255, 0xffff0000, v213
	v_lshlrev_b32_e32 v162, 16, v215
	v_and_b32_e32 v163, 0xffff0000, v215
	v_pk_add_f32 v[252:253], v[252:253], v[160:161]
	v_pk_add_f32 v[254:255], v[254:255], v[162:163]
	v_pk_add_f32 v[36:37], v[36:37], v[252:253]
	v_pk_add_f32 v[38:39], v[38:39], v[254:255]
	v_cvt_pk_bf16_f32 v212, v36, v37
	v_cvt_pk_bf16_f32 v213, v38, v39
	v_lshlrev_b32_e32 v252, 16, v212
	v_and_b32_e32 v253, 0xffff0000, v212
	v_lshlrev_b32_e32 v254, 16, v213
	v_and_b32_e32 v255, 0xffff0000, v213
	v_pk_add_f32 v[36:37], v[36:37], v[252:253] neg_lo:[0,1] neg_hi:[0,1]
	v_pk_add_f32 v[38:39], v[38:39], v[254:255] neg_lo:[0,1] neg_hi:[0,1]
	v_cvt_pk_bf16_f32 v214, v36, v37
	v_cvt_pk_bf16_f32 v215, v38, v39
	global_store_dwordx2 v246, v[212:213], s[44:45] offset:64
	global_store_dwordx2 v246, v[214:215], s[50:51] offset:64
	s_waitcnt vmcnt(38)
	v_lshlrev_b32_e32 v252, 16, v216
	v_and_b32_e32 v253, 0xffff0000, v216
	v_lshlrev_b32_e32 v160, 16, v218
	v_and_b32_e32 v161, 0xffff0000, v218
	v_lshlrev_b32_e32 v254, 16, v217
	v_and_b32_e32 v255, 0xffff0000, v217
	v_lshlrev_b32_e32 v162, 16, v219
	v_and_b32_e32 v163, 0xffff0000, v219
	v_pk_add_f32 v[252:253], v[252:253], v[160:161]
	v_pk_add_f32 v[254:255], v[254:255], v[162:163]
	v_pk_add_f32 v[8:9], v[8:9], v[252:253]
	v_pk_add_f32 v[10:11], v[10:11], v[254:255]
	v_cvt_pk_bf16_f32 v216, v8, v9
	v_cvt_pk_bf16_f32 v217, v10, v11
	v_lshlrev_b32_e32 v252, 16, v216
	v_and_b32_e32 v253, 0xffff0000, v216
	v_lshlrev_b32_e32 v254, 16, v217
	v_and_b32_e32 v255, 0xffff0000, v217
	v_pk_add_f32 v[8:9], v[8:9], v[252:253] neg_lo:[0,1] neg_hi:[0,1]
	v_pk_add_f32 v[10:11], v[10:11], v[254:255] neg_lo:[0,1] neg_hi:[0,1]
	v_cvt_pk_bf16_f32 v218, v8, v9
	v_cvt_pk_bf16_f32 v219, v10, v11
	global_store_dwordx2 v246, v[216:217], s[44:45] offset:96
	global_store_dwordx2 v246, v[218:219], s[50:51] offset:96
	s_mov_b64 exec, s[6:7]

;     ...
;     auto store = [&](const u32x4 (&ra)[4], const u32x4 (&rb)[2], const u32x4& rx, int buf) {
; #pragma unroll
;       for (int i = 0; i < 4; ++i) {
;         if (RS) ss[i] += sumsq8(__builtin_bit_cast(bf16x8, ra[i]));
;         *(u32x4*)(As + buf * ASTG + i * 4096 + soff) = ra[i];
;       }
; #pragma unroll
;       for (int i = 0; i < 2; ++i) *(u32x4*)(Bs + buf * 16384 + i * 8192 + woff) = rb[i];
;       if (TI == 5) {
;         if (RS) ss[4] += sumsq8(__builtin_bit_cast(bf16x8, rx));
;         if (srow == 0) *(u32x4*)(Ax0 + buf * 128 + ((tid & 7) << 4)) = rx;
;       }
;     ...
; #pragma unroll
;       for (int a = 0; a < 4; ++a)
; #pragma unroll
;         for (int b = 0; b < TI; ++b) acc[a][b] = (f32x4){0.f, 0.f, 0.f, 0.f};
;       c_id += G;
.LBB0_1821:
	s_load_dwordx2 s[4:5], s[0:1], 0x110
	v_mov_b32_e32 v13, v12
	v_mov_b32_e32 v14, v12
	v_mov_b32_e32 v15, v12
	v_mov_b32_e32 v139, 0
	v_mov_b64_e32 v[110:111], v[14:15]
	v_mov_b64_e32 v[90:91], v[14:15]
	v_mov_b64_e32 v[38:39], v[14:15]
	v_mov_b64_e32 v[8:9], v[12:13]
	s_waitcnt lgkmcnt(0)
	s_add_i32 s12, s12, s4
	s_lshr_b32 s100, s12, 6
	s_lshl_b32 s100, s100, 3
	s_and_b32 s101, s12, 7
	s_or_b32 s100, s100, s101
	s_mulk_i32 s100, 0x102
	s_add_i32 s100, s100, s30
	s_lshl_b32 s100, s100, 11
	s_bfe_u32 s101, s12, 0x30003
	s_lshl_b32 s101, s101, 8
	s_add_i32 s100, s100, s101
	s_mov_b32 s8, 0
	v_mov_b32_e32 v138, v139
	v_mov_b32_e32 v137, v139
	v_mov_b32_e32 v136, v139
	v_mov_b32_e32 v135, v139
	v_mov_b32_e32 v134, v139
	v_mov_b32_e32 v133, v139
	v_mov_b32_e32 v132, v139
	v_mov_b32_e32 v131, v139
	v_mov_b32_e32 v130, v139
	v_mov_b32_e32 v129, v139
	v_mov_b32_e32 v128, v139
	v_mov_b32_e32 v127, v139
	v_mov_b32_e32 v126, v139
	v_mov_b32_e32 v125, v139
	v_mov_b32_e32 v124, v139
	v_mov_b32_e32 v123, v139
	v_mov_b32_e32 v122, v139
	v_mov_b32_e32 v121, v139
	v_mov_b32_e32 v120, v139
	v_mov_b32_e32 v119, v139
	v_mov_b32_e32 v118, v139
	v_mov_b32_e32 v117, v139
	v_mov_b32_e32 v116, v139
	v_mov_b32_e32 v115, v139
	v_mov_b32_e32 v114, v139
	v_mov_b32_e32 v113, v139
	v_mov_b32_e32 v112, v139
	v_mov_b32_e32 v107, v139
	v_mov_b32_e32 v106, v139
	v_mov_b32_e32 v105, v139
	v_mov_b32_e32 v104, v139
	v_mov_b32_e32 v103, v139
	v_mov_b32_e32 v102, v139
	v_mov_b32_e32 v101, v139
	v_mov_b32_e32 v100, v139
	v_mov_b32_e32 v99, v139
	v_mov_b32_e32 v98, v139
	v_mov_b32_e32 v97, v139
	v_mov_b32_e32 v96, v139
	v_mov_b32_e32 v95, v139
	v_mov_b32_e32 v94, v139
	v_mov_b32_e32 v93, v139
	v_mov_b32_e32 v92, v139
	v_mov_b32_e32 v87, v139
	v_mov_b32_e32 v86, v139
	v_mov_b32_e32 v85, v139
	v_mov_b32_e32 v84, v139
	v_mov_b32_e32 v83, v139
	v_mov_b32_e32 v82, v139
	v_mov_b32_e32 v81, v139
	v_mov_b32_e32 v80, v139
	v_mov_b32_e32 v79, v139
	v_mov_b32_e32 v78, v139
	v_mov_b32_e32 v77, v139
	v_mov_b32_e32 v76, v139
	v_mov_b32_e32 v75, v139
	v_mov_b32_e32 v74, v139
	v_mov_b32_e32 v73, v139
	v_mov_b32_e32 v72, v139
	v_mov_b32_e32 v71, v139
	v_mov_b32_e32 v70, v139
	v_mov_b32_e32 v69, v139
	v_mov_b32_e32 v68, v139
	v_mov_b64_e32 v[108:109], v[12:13]
	v_mov_b64_e32 v[88:89], v[12:13]
	v_mov_b64_e32 v[36:37], v[12:13]
	v_mov_b64_e32 v[10:11], v[14:15]
.LBB0_1822:
	s_waitcnt vmcnt(17)
	ds_write_b128 v178, v[40:43]
	s_waitcnt vmcnt(16)
	ds_write_b128 v178, v[44:47] offset:4096
	s_waitcnt vmcnt(15)
	ds_write_b128 v178, v[48:51] offset:8192
	s_waitcnt vmcnt(14)
	ds_write_b128 v178, v[52:55] offset:12288
	s_waitcnt vmcnt(13)
	ds_write_b128 v177, v[56:59] offset:32768
	s_waitcnt vmcnt(12)
	ds_write_b128 v177, v[60:63] offset:40960
	s_and_saveexec_b64 s[4:5], s[38:39]
	s_cbranch_execz .LBB0_1779
	s_waitcnt vmcnt(11)
	ds_write_b128 v202, v[64:67]
	s_branch .LBB0_1779
